# structural-zero skipping in the lora GEMM: each unit runs one two-tile K iteration over the half of K that holds its section's weights (k<128 for sections 0/1, k>=128 for section 2); bit-identical
# speedup vs baseline: 1.0143x; 1.0064x over previous
.LBB0_614:
	s_and_b64 vcc, exec, s[0:1]
	s_cbranch_vccz .LBB0_875
	s_cmp_gt_i32 s66, 1
	s_mov_b64 s[0:1], -1
	s_cbranch_scc0 .LBB0_873
	s_cmp_lt_i32 s66, 3
	s_cbranch_scc1 .LBB0_760
	s_cmp_gt_i32 s66, 3
	s_mov_b32 s12, 0x82000
	s_cbranch_scc0 .LBB0_670
	v_readlane_b32 s8, v252, 37
	s_waitcnt vmcnt(0)
	v_mov_b32_e32 v18, v241
	v_readlane_b32 s9, v252, 38
	s_movk_i32 s0, 0x100
	v_readfirstlane_b32 s6, v18
	s_movk_i32 s4, 0x100
	s_andn2_b64 vcc, exec, s[8:9]
	s_cbranch_vccnz .LBB0_669
	v_lshlrev_b32_e32 v0, 4, v18
	s_waitcnt lgkmcnt(0)
	v_add_u32_e32 v1, 0x2000, v0
	v_ashrrev_i32_e32 v2, 31, v1
	v_lshrrev_b32_e32 v2, 22, v2
	v_add_u32_e32 v2, v1, v2
	v_ashrrev_i32_e32 v2, 10, v2
	v_mul_i32_i24_e32 v3, 0x400, v2
	v_sub_u32_e32 v1, v1, v3
	v_lshrrev_b32_e32 v3, 4, v1
	v_bitop3_b32 v1, v3, v1, 32 bitop3:0x6c
	v_ashrrev_i32_e32 v3, 31, v1
	v_lshrrev_b32_e32 v3, 26, v3
	v_writelane_b32 v255, s44, 43
	s_ashr_i32 s7, s6, 6
	s_ashr_i32 s5, s4, 31
	s_ashr_i32 s1, s0, 31
	v_add_u32_e32 v3, v1, v3
	v_lshlrev_b32_e32 v5, 3, v2
	v_writelane_b32 v255, s45, 44
	s_ashr_i32 s10, s6, 8
	s_lshl_b64 s[40:41], s[4:5], 8
	s_lshl_b64 s[42:43], s[0:1], 8
	s_lshl_b64 s[44:45], s[4:5], 9
	s_lshl_b64 s[46:47], s[0:1], 9
	s_lshl_b32 s8, s7, 10
	s_mul_i32 s9, s30, 0x180000
	v_readlane_b32 s12, v252, 6
	v_ashrrev_i32_e32 v4, 6, v3
	v_and_b32_e32 v5, -16, v5
	v_lshlrev_b32_e32 v2, 5, v2
	s_mul_hi_i32 s11, s30, 0x180000
	v_readlane_b32 s13, v252, 7
	s_add_u32 s9, s12, s9
	v_add_u32_e32 v5, v4, v5
	v_and_b32_e32 v12, 32, v2
	v_and_b32_e32 v2, 0xc0, v3
	s_addc_u32 s12, s13, s11
	v_and_b32_e32 v4, 3, v4
	s_mov_b32 s11, 0x7fffffe0
	v_lshrrev_b32_e32 v6, 2, v5
	v_lshlrev_b32_e32 v7, 1, v5
	v_sub_u32_e32 v1, v1, v2
	v_and_or_b32 v4, v5, s11, v4
	v_and_b32_e32 v6, 4, v6
	v_and_b32_e32 v7, 24, v7
	v_ashrrev_i16_sdwa v1, v230, sext(v1) dst_sel:DWORD dst_unused:UNUSED_PAD src0_sel:DWORD src1_sel:BYTE_0
	v_or3_b32 v4, v4, v6, v7
	v_bfe_i32 v13, v1, 0, 16
	v_mul_lo_u32 v4, v4, s0
	v_add_u32_e32 v1, v12, v13
	v_mul_lo_u32 v14, v5, s4
	v_add_lshl_u32 v136, v4, v1, 1
	v_add_lshl_u32 v138, v1, v14, 1
	v_bfe_i32 v1, v18, 27, 1
	v_lshrrev_b32_e32 v1, 22, v1
	v_add_u32_e32 v1, v0, v1
	v_and_b32_e32 v1, 0xfffffc00, v1
	v_sub_u32_e32 v0, v0, v1
	v_ashrrev_i32_e32 v2, 31, v18
	v_lshrrev_b32_e32 v1, 4, v0
	v_lshrrev_b32_e32 v2, 26, v2
	v_bitop3_b32 v1, v1, v0, 32 bitop3:0x6c
	v_ashrrev_i32_e32 v0, 31, v0
	v_add_u32_e32 v2, v18, v2
	v_lshrrev_b32_e32 v0, 26, v0
	v_ashrrev_i32_e32 v2, 6, v2
	v_add_u32_e32 v0, v1, v0
	v_lshlrev_b32_e32 v3, 3, v2
	v_ashrrev_i32_e32 v0, 6, v0
	v_and_b32_e32 v3, -16, v3
	v_add_u32_e32 v3, v0, v3
	v_and_b32_e32 v4, 3, v0
	v_and_or_b32 v4, v3, s11, v4
	v_readlane_b32 s11, v254, 8
	v_readlane_b32 s14, v254, 7
	v_mul_lo_u32 v17, v3, s4
	s_mul_i32 s11, s44, s11
	s_mul_hi_u32 s13, s44, s14
	s_lshr_b64 s[4:5], s[4:5], 23
	s_add_i32 s11, s13, s11
	s_mul_i32 s4, s4, s14
	s_add_i32 s11, s11, s4
	v_readlane_b32 s4, v254, 10
	v_readlane_b32 s15, v254, 9
	s_mul_i32 s4, s46, s4
	s_mul_hi_u32 s5, s46, s15
	v_mul_i32_i24_e32 v0, 64, v0
	s_add_i32 s13, s5, s4
	s_lshr_b64 s[4:5], s[0:1], 23
	v_lshrrev_b32_e32 v5, 2, v3
	v_lshlrev_b32_e32 v6, 1, v3
	v_sub_u32_e32 v0, v1, v0
	s_mul_i32 s4, s4, s15
	v_and_b32_e32 v5, 4, v5
	v_and_b32_e32 v6, 24, v6
	v_lshlrev_b32_e32 v2, 5, v2
	v_ashrrev_i16_sdwa v0, v230, sext(v0) dst_sel:DWORD dst_unused:UNUSED_PAD src0_sel:DWORD src1_sel:BYTE_0
	s_add_i32 s13, s13, s4
	s_mul_i32 s4, s46, s15
	v_or3_b32 v4, v4, v5, v6
	v_and_b32_e32 v15, 32, v2
	v_bfe_i32 v16, v0, 0, 16
	s_add_u32 s50, s9, s4
	v_mul_lo_u32 v4, v4, s0
	v_add_u32_e32 v0, v15, v16
	s_addc_u32 s51, s12, s13
	s_cmp_gt_u32 s15, 7
	s_cselect_b32 s99, 0x100, 0
	s_add_u32 s50, s50, s99
	s_addc_u32 s51, s51, 0
	s_add_i32 s13, s8, 0
	v_add_lshl_u32 v140, v4, v0, 1
	s_add_i32 m0, s13, 0x10000
	v_mov_b32_e32 v141, v185
	global_load_lds_dwordx4 v140, s[50:51]
	s_add_i32 m0, s13, 0x12000
	s_add_u32 s4, s50, s42
	global_load_lds_dwordx4 v136, s[50:51]
	s_addc_u32 s5, s51, s43
	s_add_i32 m0, s13, 0x14000
	v_mov_b32_e32 v137, v185
	global_load_lds_dwordx4 v140, s[4:5]
	s_add_i32 m0, s13, 0x16000
	s_mul_i32 s14, s44, s14
	v_lshl_add_u64 v[4:5], s[4:5], 0, v[140:141]
	v_lshl_add_u64 v[6:7], s[4:5], 0, v[136:137]
	global_load_lds_dwordx4 v136, s[4:5]
	v_readlane_b32 s4, v252, 35
	v_readlane_b32 s5, v252, 36
	s_add_u32 s4, s4, s14
	s_addc_u32 s5, s5, s11
	s_cmp_gt_u32 s15, 7
	s_cselect_b32 s99, 0x100, 0
	s_add_u32 s4, s4, s99
	s_addc_u32 s5, s5, 0
	s_add_i32 s14, s13, 0x2000
	v_add_lshl_u32 v142, v0, v17, 1
	s_mov_b32 m0, s13
	s_add_u32 s28, s4, s40
	v_writelane_b32 v255, s16, 41
	global_load_lds_dwordx4 v142, s[4:5]
	s_mov_b32 m0, s14
	s_addc_u32 s29, s5, s41
	s_add_i32 s15, s13, 0x4000
	v_writelane_b32 v255, s17, 42
	global_load_lds_dwordx4 v138, s[4:5]
	s_mov_b32 m0, s15
	s_add_i32 s17, s13, 0x6000
	global_load_lds_dwordx4 v142, s[28:29]
	s_mov_b32 m0, s17
	v_mov_b32_e32 v143, v185
	global_load_lds_dwordx4 v138, s[28:29]
	v_mov_b32_e32 v139, v185
	s_cmp_eq_u32 s10, 1
	s_mov_b32 s38, s67
	s_mov_b32 s16, s66
	s_mov_b64 s[34:35], s[56:57]
	v_lshl_add_u64 v[0:1], s[50:51], 0, v[140:141]
	v_lshl_add_u64 v[2:3], s[50:51], 0, v[136:137]
	v_lshl_add_u64 v[8:9], s[4:5], 0, v[142:143]
	v_lshl_add_u64 v[10:11], s[4:5], 0, v[138:139]
	s_cselect_b64 s[28:29], -1, 0
	s_cmp_lg_u32 s10, 1
	s_cbranch_scc1 .LBB0_621
	s_barrier
.LBB0_621:
	v_lshrrev_b32_e32 v20, 1, v18
	s_lshr_b32 s1, s1, 26
	v_and_b32_e32 v20, 24, v20
	v_and_b32_e32 v19, 15, v18
	s_add_i32 s1, s0, s1
	v_lshlrev_b32_e32 v21, 1, v20
	v_lshlrev_b32_e32 v18, 2, v18
	s_ashr_i32 s31, s1, 6
	s_mov_b32 s31, 2
	v_lshl_or_b32 v168, s10, 6, v19
	v_lshl_or_b32 v19, v19, 6, v21
	s_lshl_b32 s1, s10, 13
	v_and_b32_e32 v18, 32, v18
	v_bitop3_b32 v21, v19, s1, v18 bitop3:0xde
	s_lshl_b32 s1, s7, 5
	v_readlane_b32 s10, v255, 35
	s_and_b32 s1, s1, 0x60
	v_readlane_b32 s11, v255, 36
	v_readlane_b32 s52, v254, 51
	s_lshl_b32 s7, s1, 7
	s_lshl_b64 s[10:11], s[10:11], 2
	v_readlane_b32 s60, v254, 59
	v_readlane_b32 s61, v254, 60
	s_add_u32 s48, s60, s10
	v_readlane_b32 s54, v254, 53
	v_readlane_b32 s64, v254, 63
	s_addc_u32 s49, s61, s11
	v_readlane_b32 s55, v254, 54
	v_readlane_b32 s65, v255, 0
	s_add_u32 s54, s64, s10
	s_addc_u32 s55, s65, s11
	s_add_i32 m0, s13, 0x18000
	v_lshl_add_u64 v[0:1], v[0:1], 0, s[36:37]
	s_waitcnt vmcnt(2)
	s_barrier
	global_load_lds_dwordx4 v[0:1], off
	v_lshl_add_u64 v[0:1], v[2:3], 0, s[36:37]
	s_add_i32 m0, s13, 0x1a000
	s_add_i32 s92, s13, 0x8000
	global_load_lds_dwordx4 v[0:1], off
	v_lshl_add_u64 v[0:1], v[8:9], 0, s[36:37]
	s_mov_b32 m0, s92
	s_add_i32 s96, s13, 0xa000
	global_load_lds_dwordx4 v[0:1], off
	v_lshl_add_u64 v[0:1], v[10:11], 0, s[36:37]
	s_mov_b32 m0, s96
	v_readlane_b32 s58, v254, 57
	global_load_lds_dwordx4 v[0:1], off
	s_add_i32 m0, s13, 0x1c000
	v_lshl_add_u64 v[0:1], v[4:5], 0, s[36:37]
	global_load_lds_dwordx4 v[0:1], off
	v_lshl_add_u64 v[0:1], v[6:7], 0, s[36:37]
	s_add_i32 m0, s13, 0x1e000
	v_readlane_b32 s59, v254, 58
	global_load_lds_dwordx4 v[0:1], off
	s_cmp_gt_i32 s0, 63
	v_add_u32_e32 v0, v17, v15
	s_waitcnt vmcnt(6)
	s_cselect_b64 s[58:59], -1, 0
	s_add_i32 s97, s31, -2
	v_add_lshl_u32 v184, v0, v16, 1
	v_add_u32_e32 v0, v14, v12
	v_readlane_b32 s53, v254, 52
	v_readlane_b32 s56, v254, 55
	v_readlane_b32 s57, v254, 56
	v_readlane_b32 s66, v255, 1
	v_readlane_b32 s67, v255, 2
	s_cmpk_lt_u32 s6, 0x100
	v_lshl_add_u64 v[144:145], s[40:41], 0, v[184:185]
	v_add_lshl_u32 v184, v0, v13, 1
	v_bitop3_b32 v169, v19, s7, v18 bitop3:0xde
	s_cselect_b64 s[60:61], -1, 0
	v_or_b32_e32 v170, s1, v20
	v_lshl_add_u64 v[146:147], s[40:41], 0, v[184:185]
	s_mov_b32 s76, 0
	v_add_u32_e32 v171, 0, v21
	v_readlane_b32 s69, v254, 9
	v_readlane_b32 s71, v254, 7
	s_mov_b64 s[56:57], s[34:35]
	s_mov_b32 s66, s16
	s_mov_b32 s67, s38
	s_mov_b64 s[52:53], s[28:29]
	v_readlane_b32 s62, v254, 61
	v_readlane_b32 s63, v254, 62
	s_barrier
	s_branch .LBB0_624

.LBB0_630:
	v_cndmask_b32_e64 v0, 0, 1, s[0:1]
	v_cmp_ne_u32_e64 s[38:39], 1, v0
	s_andn2_b64 vcc, exec, s[0:1]
	s_mov_b64 s[0:1], s[4:5]
	s_cbranch_vccnz .LBB0_632
	s_ashr_i32 s0, s11, 31
	s_mul_hi_u32 s1, s44, s11
	s_mul_i32 s0, s44, s0
	s_add_i32 s0, s1, s0
	s_mul_i32 s1, s45, s11
	s_add_i32 s1, s0, s1
	s_mul_i32 s0, s44, s11
	v_readlane_b32 s6, v252, 35
	v_readlane_b32 s7, v252, 36
	s_add_u32 s0, s6, s0
	s_addc_u32 s1, s7, s1
	s_cmp_gt_u32 s10, 7
	s_cselect_b32 s99, 0x100, 0
	s_add_u32 s0, s0, s99
	s_addc_u32 s1, s1, 0
.LBB0_632:
	s_and_b64 vcc, exec, s[38:39]
	s_mov_b64 s[28:29], s[50:51]
	s_cbranch_vccnz .LBB0_634
	s_ashr_i32 s6, s10, 31
	s_mul_hi_u32 s7, s46, s10
	s_mul_i32 s6, s46, s6
	s_add_i32 s6, s7, s6
	s_mul_i32 s7, s47, s10
	s_add_i32 s6, s6, s7
	s_mul_i32 s7, s46, s10
	s_add_u32 s28, s9, s7
	s_addc_u32 s29, s12, s6
	s_cmp_gt_u32 s10, 7
	s_cselect_b32 s99, 0x100, 0
	s_add_u32 s28, s28, s99
	s_addc_u32 s29, s29, 0
